# latent attention: one static s_setprio 1 for waves 4-7 (younger half) per unit
# speedup vs baseline: 1.0008x; 1.0008x over previous
.LBB0_708:
	v_readfirstlane_b32 s2, v220
	s_cmp_lt_u32 s2, 0x100
	s_cbranch_scc1 .Lattn_noprio
	s_setprio 1

.LBB0_727:
	s_setprio 0
	v_readlane_b32 s2, v255, 36
	v_readlane_b32 s3, v255, 37
	s_andn2_b64 vcc, exec, s[2:3]
	v_readlane_b32 s16, v255, 49
	v_readlane_b32 s24, v255, 48
	v_mov_b64_e32 v[224:225], 0x3ff
	s_cbranch_vccz .LBB0_738
